# baseline (speedup 1.0000x reference)
.Lnl1_Ago:
	v_mov_b32_e32 v80, v55
	v_mov_b32_e32 v81, v59
	v_mov_b32_e32 v78, v54
	v_mov_b32_e32 v79, v58
	v_pk_mul_f32 v[80:81], v[80:81], v[80:81]
	v_mov_b32_e32 v74, v56
	v_mov_b32_e32 v75, v60
	v_pk_fma_f32 v[78:79], v[78:79], v[78:79], v[80:81]
	v_mov_b32_e32 v76, v57
	v_mov_b32_e32 v77, v61
	v_pk_fma_f32 v[74:75], v[74:75], v[74:75], v[78:79]
	s_nop 0
	v_pk_fma_f32 v[72:73], v[76:77], v[76:77], v[74:75]
	s_nop 0
	v_add_f32_e32 v53, v72, v73
	v_mov_b32_e32 v80, v63
	v_mov_b32_e32 v81, v67
	v_mov_b32_e32 v78, v62
	v_mov_b32_e32 v79, v66
	v_pk_mul_f32 v[80:81], v[80:81], v[80:81]
	v_mov_b32_e32 v74, v64
	v_mov_b32_e32 v75, v68
	v_pk_fma_f32 v[78:79], v[78:79], v[78:79], v[80:81]
	v_mov_b32_e32 v76, v65
	v_mov_b32_e32 v77, v69
	v_pk_fma_f32 v[74:75], v[74:75], v[74:75], v[78:79]
	s_nop 0
	v_pk_fma_f32 v[74:75], v[76:77], v[76:77], v[74:75]
	s_nop 0
	v_add_f32_e32 v53, v53, v74
	v_add_f32_e32 v53, v53, v75
	ds_bpermute_b32 v72, v44, v53
	s_waitcnt lgkmcnt(0)
	v_add_f32_e32 v53, v53, v72
	ds_bpermute_b32 v72, v45, v53
	s_waitcnt lgkmcnt(0)
	v_add_f32_e32 v53, v53, v72
	ds_bpermute_b32 v72, v46, v53
	s_waitcnt lgkmcnt(0)
	v_add_f32_e32 v53, v53, v72
	ds_bpermute_b32 v72, v47, v53
	s_waitcnt lgkmcnt(0)
	v_add_f32_e32 v53, v53, v72
	v_mov_b32_e32 v72, v53
	s_nop 1
	v_permlane16_swap_b32_e32 v72, v53
	s_nop 0
	v_add_f32_e32 v53, v53, v72
	v_mov_b32_e32 v72, v53
	s_nop 1
	v_permlane32_swap_b32_e32 v72, v53
	s_nop 0
	v_add_f32_e32 v53, v53, v72
	v_fmamk_f32 v53, v53, 0x3a800000, v149
	v_cmp_gt_f32_e32 vcc, s26, v53
	v_mul_f32_e32 v72, 0x4b800000, v53
	s_nop 0
	v_cndmask_b32_e32 v53, v53, v72, vcc
	v_rsq_f32_e32 v53, v53
	s_nop 0
	v_mul_f32_e32 v72, 0x45800000, v53
	v_cndmask_b32_e32 v72, v53, v72, vcc
	v_pk_mul_f32 v[54:55], v[72:73], v[54:55] op_sel_hi:[0,1]
	v_pk_mul_f32 v[56:57], v[72:73], v[56:57] op_sel_hi:[0,1]
	v_pk_fma_f32 v[54:55], v[54:55], v[28:29], v[2:3]
	v_pk_fma_f32 v[56:57], v[56:57], v[30:31], v[4:5]
	v_cvt_pk_bf16_f32 v54, v54, v55
	v_cvt_pk_bf16_f32 v55, v56, v57
	global_store_dwordx2 v[70:71], v[54:55], off offset:-1024
	v_pk_mul_f32 v[54:55], v[72:73], v[58:59] op_sel_hi:[0,1]
	v_pk_mul_f32 v[56:57], v[72:73], v[60:61] op_sel_hi:[0,1]
	v_pk_fma_f32 v[54:55], v[54:55], v[32:33], v[6:7]
	v_pk_fma_f32 v[56:57], v[56:57], v[34:35], v[8:9]
	v_cvt_pk_bf16_f32 v54, v54, v55
	v_cvt_pk_bf16_f32 v55, v56, v57
	global_store_dwordx2 v[70:71], v[54:55], off offset:-512
	v_pk_mul_f32 v[54:55], v[72:73], v[62:63] op_sel_hi:[0,1]
	v_pk_mul_f32 v[56:57], v[72:73], v[64:65] op_sel_hi:[0,1]
	v_pk_fma_f32 v[54:55], v[54:55], v[36:37], v[10:11]
	v_pk_fma_f32 v[56:57], v[56:57], v[38:39], v[12:13]
	v_cvt_pk_bf16_f32 v54, v54, v55
	v_cvt_pk_bf16_f32 v55, v56, v57
	global_store_dwordx2 v[70:71], v[54:55], off
	v_pk_mul_f32 v[54:55], v[72:73], v[66:67] op_sel_hi:[0,1]
	v_pk_mul_f32 v[56:57], v[72:73], v[68:69] op_sel_hi:[0,1]
	v_pk_fma_f32 v[54:55], v[54:55], v[40:41], v[14:15]
	v_pk_fma_f32 v[56:57], v[56:57], v[42:43], v[16:17]
	v_cvt_pk_bf16_f32 v54, v54, v55
	v_cvt_pk_bf16_f32 v55, v56, v57
	global_store_dwordx2 v[70:71], v[54:55], off offset:512
	s_add_u32 s6, s6, 0x800
	s_addc_u32 s7, s7, 0
	v_lshl_add_u64 v[70:71], v[26:27], 0, s[6:7]
	s_cmpk_eq_u32 s6, 0x7800
	s_cbranch_scc1 .Lnl1_Blast
	v_lshl_add_u64 v[24:25], v[24:25], 0, s[48:49]
	global_load_dwordx4 v[54:57], v[24:25], off offset:-2048
	global_load_dwordx4 v[58:61], v[24:25], off offset:-1024
	global_load_dwordx4 v[62:65], v[24:25], off
	global_load_dwordx4 v[66:69], v[24:25], off offset:1024
	s_waitcnt vmcnt(8)
	s_branch .Lnl1_Bgo

.Lnl1_Bgo:
	v_mov_b32_e32 v80, v83
	v_mov_b32_e32 v81, v87
	v_mov_b32_e32 v78, v82
	v_mov_b32_e32 v79, v86
	v_pk_mul_f32 v[80:81], v[80:81], v[80:81]
	v_mov_b32_e32 v74, v84
	v_mov_b32_e32 v75, v88
	v_pk_fma_f32 v[78:79], v[78:79], v[78:79], v[80:81]
	v_mov_b32_e32 v76, v85
	v_mov_b32_e32 v77, v89
	v_pk_fma_f32 v[74:75], v[74:75], v[74:75], v[78:79]
	s_nop 0
	v_pk_fma_f32 v[72:73], v[76:77], v[76:77], v[74:75]
	s_nop 0
	v_add_f32_e32 v53, v72, v73
	v_mov_b32_e32 v80, v91
	v_mov_b32_e32 v81, v95
	v_mov_b32_e32 v78, v90
	v_mov_b32_e32 v79, v94
	v_pk_mul_f32 v[80:81], v[80:81], v[80:81]
	v_mov_b32_e32 v74, v92
	v_mov_b32_e32 v75, v96
	v_pk_fma_f32 v[78:79], v[78:79], v[78:79], v[80:81]
	v_mov_b32_e32 v76, v93
	v_mov_b32_e32 v77, v97
	v_pk_fma_f32 v[74:75], v[74:75], v[74:75], v[78:79]
	s_nop 0
	v_pk_fma_f32 v[74:75], v[76:77], v[76:77], v[74:75]
	s_nop 0
	v_add_f32_e32 v53, v53, v74
	v_add_f32_e32 v53, v53, v75
	ds_bpermute_b32 v72, v44, v53
	s_waitcnt lgkmcnt(0)
	v_add_f32_e32 v53, v53, v72
	ds_bpermute_b32 v72, v45, v53
	s_waitcnt lgkmcnt(0)
	v_add_f32_e32 v53, v53, v72
	ds_bpermute_b32 v72, v46, v53
	s_waitcnt lgkmcnt(0)
	v_add_f32_e32 v53, v53, v72
	ds_bpermute_b32 v72, v47, v53
	s_waitcnt lgkmcnt(0)
	v_add_f32_e32 v53, v53, v72
	v_mov_b32_e32 v72, v53
	s_nop 1
	v_permlane16_swap_b32_e32 v72, v53
	s_nop 0
	v_add_f32_e32 v53, v53, v72
	v_mov_b32_e32 v72, v53
	s_nop 1
	v_permlane32_swap_b32_e32 v72, v53
	s_nop 0
	v_add_f32_e32 v53, v53, v72
	v_fmamk_f32 v53, v53, 0x3a800000, v149
	v_cmp_gt_f32_e32 vcc, s26, v53
	v_mul_f32_e32 v72, 0x4b800000, v53
	s_nop 0
	v_cndmask_b32_e32 v53, v53, v72, vcc
	v_rsq_f32_e32 v53, v53
	s_nop 0
	v_mul_f32_e32 v72, 0x45800000, v53
	v_cndmask_b32_e32 v72, v53, v72, vcc
	v_pk_mul_f32 v[82:83], v[72:73], v[82:83] op_sel_hi:[0,1]
	v_pk_mul_f32 v[84:85], v[72:73], v[84:85] op_sel_hi:[0,1]
	v_pk_fma_f32 v[82:83], v[82:83], v[28:29], v[2:3]
	v_pk_fma_f32 v[84:85], v[84:85], v[30:31], v[4:5]
	v_cvt_pk_bf16_f32 v82, v82, v83
	v_cvt_pk_bf16_f32 v83, v84, v85
	global_store_dwordx2 v[70:71], v[82:83], off offset:-1024
	v_pk_mul_f32 v[82:83], v[72:73], v[86:87] op_sel_hi:[0,1]
	v_pk_mul_f32 v[84:85], v[72:73], v[88:89] op_sel_hi:[0,1]
	v_pk_fma_f32 v[82:83], v[82:83], v[32:33], v[6:7]
	v_pk_fma_f32 v[84:85], v[84:85], v[34:35], v[8:9]
	v_cvt_pk_bf16_f32 v82, v82, v83
	v_cvt_pk_bf16_f32 v83, v84, v85
	global_store_dwordx2 v[70:71], v[82:83], off offset:-512
	v_pk_mul_f32 v[82:83], v[72:73], v[90:91] op_sel_hi:[0,1]
	v_pk_mul_f32 v[84:85], v[72:73], v[92:93] op_sel_hi:[0,1]
	v_pk_fma_f32 v[82:83], v[82:83], v[36:37], v[10:11]
	v_pk_fma_f32 v[84:85], v[84:85], v[38:39], v[12:13]
	v_cvt_pk_bf16_f32 v82, v82, v83
	v_cvt_pk_bf16_f32 v83, v84, v85
	global_store_dwordx2 v[70:71], v[82:83], off
	v_pk_mul_f32 v[82:83], v[72:73], v[94:95] op_sel_hi:[0,1]
	v_pk_mul_f32 v[84:85], v[72:73], v[96:97] op_sel_hi:[0,1]
	v_pk_fma_f32 v[82:83], v[82:83], v[40:41], v[14:15]
	v_pk_fma_f32 v[84:85], v[84:85], v[42:43], v[16:17]
	v_cvt_pk_bf16_f32 v82, v82, v83
	v_cvt_pk_bf16_f32 v83, v84, v85
	global_store_dwordx2 v[70:71], v[82:83], off offset:512
	s_add_u32 s6, s6, 0x800
	s_addc_u32 s7, s7, 0
	s_cmpk_eq_u32 s6, 0x8000
	s_cbranch_scc0 .Lnl1_A
	s_add_i32 s4, s4, s3
	s_cmpk_gt_i32 s4, 0xff
	s_cbranch_scc0 .LBB0_119
